# last layer: dead meta rows skipped in the two row passes and the dead gate-column round of the P1 skinny GEMM skipped (on top of the skinny-GEMM skip)
# speedup vs baseline: 1.0198x; 1.0056x over previous
; #define MFMA16(a, b, c) __builtin_amdgcn_mfma_f32_16x16x32_bf16((a), (b), (c), 0, 0, 0)
;     __device__ __forceinline__ void apply(int row, int tile, int g, f32x4 v, f32x4) const { *(u32x2*)(O + (size_t)row * D + 16 * tile + 4 * g) = pack4(v); }
; template <class SE> __device__ __forceinline__ void skinny_gemm(const Frame& F, const bf16* Am, const bf16* Bt, int ntiles, int K, const SE& E) {
;     ...
;     for (int tile = F.bx; tile < ntiles; tile += F.G) {
;         const bf16* ap = Am + (size_t)j * K + 8 * g;
;         const bf16* b0 = Bt + (size_t)(E.brow(tile, 0) + j) * K + 8 * g;
;         const bf16* b1 = Bt + (size_t)(E.brow(tile, 1) + j) * K + 8 * g;
;         f32x4 acc0 = {0.f, 0.f, 0.f, 0.f}, acc1 = {0.f, 0.f, 0.f, 0.f};
; #pragma unroll 1
;         for (int s0 = sb; s0 < se; s0 += 8) {
;             const int n = (se - s0) < 8 ? (se - s0) : 8;
;             bf16x8 av[8], bv[8], cv[8];
; #pragma unroll
;             for (int q = 0; q < 8; ++q) if (q < n) { av[q] = *(const bf16x8*)(ap + 32 * (s0 + q)); bv[q] = *(const bf16x8*)(b0 + 32 * (s0 + q)); if (SE::DUAL) cv[q] = *(const bf16x8*)(b1 + 32 * (s0 + q)); }
; #pragma unroll
;             for (int q = 0; q < 8; ++q) if (q < n) { acc0 = MFMA16(bv[q], av[q], acc0); if (SE::DUAL) acc1 = MFMA16(cv[q], av[q], acc1); }
;         }
;         part[w * 64 + F.lane] = acc0; if (SE::DUAL) part[512 + w * 64 + F.lane] = acc1;
;         asm volatile("s_waitcnt lgkmcnt(0)" ::: "memory"); __builtin_amdgcn_s_barrier(); asm volatile("" ::: "memory");
;         if (w == 0) {
;             f32x4 t0 = part[F.lane], t1 = {0.f, 0.f, 0.f, 0.f}; if (SE::DUAL) t1 = part[512 + F.lane];
; #pragma unroll
;             for (int ww = 1; ww < 8; ++ww) { t0 += part[ww * 64 + F.lane]; if (SE::DUAL) t1 += part[512 + ww * 64 + F.lane]; }
;             E.apply(MF + j, tile, g, t0, t1);
;         }
;         asm volatile("s_waitcnt lgkmcnt(0)" ::: "memory"); __builtin_amdgcn_s_barrier(); asm volatile("" ::: "memory");
.LBB0_181:
	s_waitcnt lgkmcnt(0)
	s_barrier
	s_add_i32 s66, s66, s82
	v_readlane_b32 s98, v255, 52
	s_and_b32 s98, s98, 0x100
	s_add_i32 s98, s98, 0x300
	s_cmp_lt_i32 s66, s98
	s_cbranch_scc0 .LBB0_259

; __device__ __forceinline__ float bflo(unsigned w) { return __uint_as_float(w << 16); }
; __device__ __forceinline__ float bfhi(unsigned w) { return __uint_as_float(w & 0xffff0000u); }
; __device__ __forceinline__ void rowpass_res(const Frame& F, const Params& p, const float* gpost, const float* gnext, bool first, bool last) {
;     ...
;     for (int r0 = 2 * F.gw; r0 < MREAL; r0 += 2 * F.ngw) {
;         f32x4 v[2][8]; float ss[2] = {0.f, 0.f};
; #pragma unroll
;         for (int u = 0; u < 2; ++u) { const bf16* ms = Msrc + (size_t)(r0 + u) * D;
; #pragma unroll
;             for (int j = 0; j < 8; ++j) { const u32x2 mw = *(const u32x2*)(ms + 4 * F.lane + 256 * j); v[u][j] = (f32x4){bflo(mw.x), bfhi(mw.x), bflo(mw.y), bfhi(mw.y)}; } }
;         f32x4 hv[2][8];
; #pragma unroll
;         for (int u = 0; u < 2; ++u) { const int r = r0 + u; const bf16* hb = HB + (size_t)r * D;
.LBB0_852:
	s_cmpk_lt_i32 s2, 0x4000
	s_cbranch_scc1 .Lrp6_go
	v_readlane_b32 s98, v255, 52
	s_cmp_eq_u32 s98, 0
	s_cbranch_scc1 .LBB0_918

; __device__ __forceinline__ unsigned cvt_pk_bf16(float lo, float hi) { cvt_f32x2_t v = {lo, hi}; cvt_bf16x2_t b = __builtin_convertvector(v, cvt_bf16x2_t); return __builtin_bit_cast(unsigned, b); }
; __device__ __forceinline__ void rowpass_res(const Frame& F, const Params& p, const float* gpost, const float* gnext, bool first, bool last) {
;     ...
;     for (int r0 = 2 * F.gw; r0 < MREAL; r0 += 2 * F.ngw) {
;         f32x4 v[2][8]; float ss[2] = {0.f, 0.f};
;     ...
;                 if (last) { if (r < MF) *(f32x4*)(p.out + (size_t)r * D + 4 * F.lane + 256 * j) = v[u][j]; }
;                 else { u32x2 w; w.x = cvt_pk_bf16(v[u][j].x, v[u][j].y); w.y = cvt_pk_bf16(v[u][j].z, v[u][j].w); *(u32x2*)(hb + 4 * F.lane + 256 * j) = w; }
;                 ss2[u] += (v[u][j].x * v[u][j].x + v[u][j].y * v[u][j].y) + (v[u][j].z * v[u][j].z + v[u][j].w * v[u][j].w); } }
;         if (gnext) {
.LBB0_1204:
	s_cmpk_lt_i32 s6, 0x4000
	s_cbranch_scc1 .Lrp9_go
	s_cmp_eq_u64 s[66:67], 0
	s_cbranch_scc1 .LBB0_1286
